# P7 first half: per-token address arithmetic folded into load offset immediates (64 fewer 64-bit address instructions per iteration)
# baseline (speedup 1.0000x reference)
; #define LAS __attribute__((address_space(3)))
; __device__ __forceinline__ float bf2f(bf16_t b) { return __uint_as_float(((unsigned)b) << 16); }
; #define ZACC(a) do { a[0] = (f32x4){0.f, 0.f, 0.f, 0.f}; a[1] = (f32x4){0.f, 0.f, 0.f, 0.f}; } while (0)
; __device__ __forceinline__ void rwkv_phase_c(const Ctx& C) {
;     ...
;             if (cc + 1 < GCH) { const f32x4* P4 = (const f32x4*)(Pg + io + 8 * 4096); n0 = P4[e0]; n1 = P4[e1]; rn = ((const u32x4*)(Rcg + io + 8 * 4096))[tid]; }
;             float qv[2][4], yv[2][4];
; #pragma unroll
;             for (int i = 0; i < 2; ++i)
; #pragma unroll
;                 for (int j = 0; j < 4; ++j) { const int r = mt * 16 + 4 * q + j, c2 = nc0 + 16 * i; qv[i][j] = Qi[r * 64 + c2]; yv[i][j] = bf2f(Yi[r * 64 + c2]); }
;             float vv[8], bo[8], gt[8];
; #pragma unroll
;             for (int u = 0; u < 8; ++u) { const int tok = tok0 + tg8 * 8 + u; vv[u] = zshift(zr, tok, 1024 + h * 64 + ci, muv); bo[u] = bon[(size_t)tok * 8 + h]; gt[u] = bf2f(Gg[(size_t)tok * GWD_ + h * 64 + ci]); }
;             f32x4 xy[2], xs[2]; ZACC(xy); ZACC(xs);
; #pragma unroll
;             for (int ks = 0; ks < 2; ++ks) {
;                 const bf16x8 a = *(const LAS bf16x8*)(Rb + mrow * BS + ks * 32 + q * 8);
;                 const bf16x8 h0 = *(const LAS bf16x8*)(SH + nc0 * BS + ks * 32 + q * 8), h1 = *(const LAS bf16x8*)(SH + (nc0 + 16) * BS + ks * 32 + q * 8);
;                 const bf16x8 l0 = *(const LAS bf16x8*)(SL + nc0 * BS + ks * 32 + q * 8), l1 = *(const LAS bf16x8*)(SL + (nc0 + 16) * BS + ks * 32 + q * 8);
;                 xy[0] = __builtin_amdgcn_mfma_f32_16x16x32_bf16(a, h0, xy[0], 0, 0, 0); xy[1] = __builtin_amdgcn_mfma_f32_16x16x32_bf16(a, h1, xy[1], 0, 0, 0);
;                 xy[0] = __builtin_amdgcn_mfma_f32_16x16x32_bf16(a, l0, xy[0], 0, 0, 0); xy[1] = __builtin_amdgcn_mfma_f32_16x16x32_bf16(a, l1, xy[1], 0, 0, 0);
;             }
;             mm_lds<false>(xs, MAT(0), Pb, mrow, nc0, q);
.LBB0_1066:
	s_mov_b64 s[68:69], 0x800
	s_mov_b64 s[70:71], 0x3200
	s_mov_b64 s[98:99], 0x5c00
	s_mov_b64 s[100:101], 0x1000
	s_add_i32 s11, s51, -1
	s_lshl_b64 s[14:15], s[16:17], 2
	s_add_u32 s14, s0, s14
	s_addc_u32 s15, s1, s15
	s_lshl_b64 s[16:17], s[16:17], 1
	s_add_u32 s16, s2, s16
	s_addc_u32 s17, s3, s17
	ds_read_b128 v[30:33], v77
	s_bitcmp1_b32 s11, 0
	s_cselect_b32 s42, 0x4400, 0
	v_add_u32_e32 v168, s42, v74
	v_add_u32_e32 v81, 0x8800, v168
	ds_read2_b32 v[42:43], v81 offset1:16
	ds_read_b128 v[34:37], v77 offset:64
	s_waitcnt lgkmcnt(1)
	v_mfma_f32_16x16x4_f32 v[38:41], v30, v42, 0
	v_lshl_add_u64 v[88:89], v[24:25], 1, s[16:17]
	v_lshl_add_u64 v[90:91], v[26:27], 1, s[16:17]
	v_lshl_add_u64 v[94:95], v[28:29], 1, s[16:17]
	ds_read2_b32 v[86:87], v81 offset0:204 offset1:220
	v_lshl_add_u64 v[92:93], v[28:29], 2, s[14:15]
	s_or_b32 s11, s11, 6
	s_mulk_i32 s11, 0x4400
	v_mfma_f32_16x16x4_f32 v[82:85], v30, v43, 0
	ds_read2_b32 v[42:43], v81 offset0:68 offset1:84
	s_andn2_b64 vcc, exec, s[6:7]
	s_waitcnt lgkmcnt(0)
	v_mfma_f32_16x16x4_f32 v[38:41], v31, v42, v[38:41]
	v_mfma_f32_16x16x4_f32 v[82:85], v31, v43, v[82:85]
	ds_read2_b32 v[30:31], v81 offset0:136 offset1:152
	v_lshl_add_u64 v[42:43], v[24:25], 2, s[14:15]
	s_waitcnt lgkmcnt(0)
	v_mfma_f32_16x16x4_f32 v[38:41], v32, v30, v[38:41]
	v_mfma_f32_16x16x4_f32 v[82:85], v32, v31, v[82:85]
	v_lshl_add_u64 v[30:31], v[14:15], 1, s[16:17]
	global_load_ushort v185, v[90:91], off
	global_load_ushort v186, v[94:95], off
	global_load_ushort v187, v[30:31], off
	global_load_ushort v188, v[88:89], off
	s_nop 0
	global_load_ushort v189, v[88:89], off offset:32
	s_nop 0
	global_load_dword v169, v[42:43], off offset:64
	global_load_ushort v190, v[30:31], off offset:32
	s_nop 0
	global_load_ushort v191, v[94:95], off offset:32
	s_nop 0
	global_load_dword v170, v[92:93], off offset:64
	s_nop 0
	global_load_ushort v192, v[90:91], off offset:32
	v_add_u32_e32 v91, 0x9800, v168
	v_mfma_f32_16x16x4_f32 v[38:41], v33, v86, v[38:41]
	v_mfma_f32_16x16x4_f32 v[30:33], v33, v87, v[82:85]
	ds_read2_b32 v[82:83], v91 offset0:64 offset1:80
	v_lshl_add_u64 v[84:85], v[14:15], 2, s[14:15]
	v_lshl_add_u64 v[86:87], v[26:27], 2, s[14:15]
	global_load_dword v171, v[42:43], off
	global_load_dword v172, v[84:85], off
	global_load_dword v173, v[84:85], off offset:64
	global_load_dword v174, v[92:93], off
	global_load_dword v175, v[86:87], off
	global_load_dword v176, v[86:87], off offset:64
	v_add_u32_e32 v42, s54, v76
	v_ashrrev_i32_e32 v43, 31, v42
	v_mad_i64_i32 v[200:201], s[14:15], v42, s47, v[18:19]
	v_max_i32_e32 v216, 1, v42
	v_add_u32_e32 v216, -1, v216
	v_mad_u64_u32 v[202:203], s[14:15], v216, s47, v[18:19]
	v_lshl_add_u64 v[204:205], v[200:201], 0, s[68:69]
	v_lshl_add_u64 v[206:207], v[200:201], 0, s[70:71]
	v_lshl_add_u64 v[208:209], v[200:201], 0, s[98:99]
	v_lshlrev_b64 v[210:211], 10, v[42:43]
	v_lshl_add_u64 v[210:211], v[20:21], 0, v[210:211]
	v_lshl_add_u64 v[212:213], v[210:211], 0, s[100:101]
	v_lshlrev_b64 v[214:215], 5, v[42:43]
	v_lshl_add_u64 v[214:215], s[12:13], 0, v[214:215]
	s_waitcnt lgkmcnt(0)
	v_mfma_f32_16x16x4_f32 v[38:41], v34, v82, v[38:41]
	v_mfma_f32_16x16x4_f32 v[30:33], v34, v83, v[30:33]
	ds_read2_b32 v[82:83], v91 offset0:132 offset1:148
	v_add_u32_e32 v81, 0xa800, v168
	s_waitcnt lgkmcnt(0)
	v_mfma_f32_16x16x4_f32 v[38:41], v35, v82, v[38:41]
	v_mfma_f32_16x16x4_f32 v[30:33], v35, v83, v[30:33]
	ds_read2_b32 v[34:35], v91 offset0:200 offset1:216
	s_waitcnt lgkmcnt(0)
	v_mfma_f32_16x16x4_f32 v[82:85], v36, v34, v[38:41]
	s_nop 3
	v_add_u32_e32 v40, 1, v42
	v_ashrrev_i32_e32 v41, 31, v40
	v_mfma_f32_16x16x4_f32 v[30:33], v36, v35, v[30:33]
	v_add_u32_e32 v36, 0x9c00, v168
	ds_read2_b32 v[94:95], v36 offset0:12 offset1:28
	s_waitcnt lgkmcnt(0)
	v_mfma_f32_16x16x4_f32 v[82:85], v37, v94, v[82:85]
	global_load_ushort v94, v[204:205], off
	global_load_ushort v93, v[202:203], off offset:2048
	s_nop 0
	global_load_dword v88, v[214:215], off
	s_nop 0
	global_load_ushort v91, v[210:211], off
	global_load_ushort v92, v[204:205], off offset:3584
	global_load_ushort v90, v[204:205], off
	global_load_dword v87, v[214:215], off offset:32
	global_load_ushort v89, v[210:211], off offset:1024
	ds_read_b128 v[98:101], v77 offset:128
	ds_read_b128 v[112:115], v77 offset:192
	ds_read2_b32 v[34:35], v81 offset0:128 offset1:144
	v_add_u32_e32 v38, 2, v42
	ds_read2_b32 v[102:103], v81 offset0:196 offset1:212
	v_ashrrev_i32_e32 v39, 31, v38
	v_mfma_f32_16x16x4_f32 v[30:33], v37, v95, v[30:33]
	s_waitcnt lgkmcnt(1)
	v_mfma_f32_16x16x4_f32 v[82:85], v98, v34, v[82:85]
	v_mfma_f32_16x16x4_f32 v[30:33], v98, v35, v[30:33]
	v_add_u32_e32 v36, 3, v42
	v_ashrrev_i32_e32 v37, 31, v36
	s_waitcnt lgkmcnt(0)
	v_mfma_f32_16x16x4_f32 v[106:109], v99, v102, v[82:85]
	v_add_u32_e32 v81, 0xac00, v168
	v_mfma_f32_16x16x4_f32 v[30:33], v99, v103, v[30:33]
	global_load_ushort v103, v[206:207], off offset:-3584
	s_nop 0
	global_load_ushort v104, v[204:205], off offset:3584
	s_nop 0
	global_load_dword v86, v[214:215], off offset:64
	global_load_ushort v97, v[210:211], off offset:2048
	global_load_ushort v98, v[206:207], off
	global_load_ushort v99, v[206:207], off offset:-3584
	s_nop 0
	global_load_dword v85, v[214:215], off offset:96
	s_nop 0
	global_load_ushort v96, v[210:211], off offset:3072
	ds_read2_b32 v[82:83], v81 offset0:8 offset1:24
	v_add_u32_e32 v34, 4, v42
	v_ashrrev_i32_e32 v35, 31, v34
	s_waitcnt lgkmcnt(0)
	v_mfma_f32_16x16x4_f32 v[106:109], v100, v82, v[106:109]
	v_mfma_f32_16x16x4_f32 v[116:119], v100, v83, v[30:33]
	ds_read2_b32 v[82:83], v81 offset0:76 offset1:92
	v_add_u32_e32 v32, 5, v42
	v_ashrrev_i32_e32 v33, 31, v32
	s_waitcnt lgkmcnt(0)
; #define LAS __attribute__((address_space(3)))
; __device__ __forceinline__ float bf2f(bf16_t b) { return __uint_as_float(((unsigned)b) << 16); }
; __device__ __forceinline__ bf16_t f2bf(float f) { return (bf16_t)(pk2(f, 0.f) & 0xffffu); }
; __device__ __forceinline__ void rwkv_phase_c(const Ctx& C) {
;     ...
; #pragma unroll
;             for (int ks = 0; ks < 2; ++ks) {
;                 const bf16x8 a = *(const LAS bf16x8*)(Rb + mrow * BS + ks * 32 + q * 8);
;                 const bf16x8 h0 = *(const LAS bf16x8*)(SH + nc0 * BS + ks * 32 + q * 8), h1 = *(const LAS bf16x8*)(SH + (nc0 + 16) * BS + ks * 32 + q * 8);
;                 const bf16x8 l0 = *(const LAS bf16x8*)(SL + nc0 * BS + ks * 32 + q * 8), l1 = *(const LAS bf16x8*)(SL + (nc0 + 16) * BS + ks * 32 + q * 8);
;                 xy[0] = __builtin_amdgcn_mfma_f32_16x16x32_bf16(a, h0, xy[0], 0, 0, 0); xy[1] = __builtin_amdgcn_mfma_f32_16x16x32_bf16(a, h1, xy[1], 0, 0, 0);
;                 xy[0] = __builtin_amdgcn_mfma_f32_16x16x32_bf16(a, l0, xy[0], 0, 0, 0); xy[1] = __builtin_amdgcn_mfma_f32_16x16x32_bf16(a, l1, xy[1], 0, 0, 0);
;             }
;             mm_lds<false>(xs, MAT(0), Pb, mrow, nc0, q);
; #pragma unroll
;             for (int i = 0; i < 2; ++i)
; #pragma unroll
;                 for (int j = 0; j < 4; ++j) { const int r = mt * 16 + 4 * q + j, c2 = nc0 + 16 * i; MAT(1)[r * MS + c2] = xy[i][j] + yv[i][j]; }
;             __syncthreads();
; #pragma unroll
;             for (int i = 0; i < 2; ++i)
; #pragma unroll
;                 for (int j = 0; j < 4; ++j) { const int r = mt * 16 + 4 * q + j, c2 = nc0 + 16 * i; const float sv = xs[i][j] + qv[i][j];
;                     MAT(0)[r * MS + c2] = sv; const bf16_t hb = f2bf(sv); SH[r * BS + c2] = hb; SL[r * BS + c2] = f2bf(sv - bf2f(hb)); }
;             if (cc + 1 < GCH) {
;                 LAS float* Pn = MAT(2 + ((cc + 1) & 1));
;                 *(LAS f32x4*)(Pn + r0 * MS + c0) = n0; *(LAS f32x4*)(Pn + r1 * MS + c1) = n1;
;                 *(LAS u32x4*)((LAS bf16_t*)MAT(6 + ((cc + 1) & 1)) + rr8 * BS + cc8) = rn;
;             }
	v_mfma_f32_16x16x4_f32 v[120:123], v101, v82, v[106:109]
	v_add_u32_e32 v81, s11, v73
	global_load_ushort v109, v[206:207], off offset:3584
	s_nop 0
	global_load_ushort v110, v[206:207], off
	global_load_dword v84, v[214:215], off offset:128
	global_load_ushort v106, v[212:213], off
	global_load_ushort v107, v[208:209], off offset:-3584
	global_load_ushort v108, v[206:207], off offset:3584
	global_load_dword v82, v[214:215], off offset:160
	global_load_ushort v105, v[212:213], off offset:1024
	ds_read_b128 v[124:127], v81
	ds_read_b128 v[128:131], v53
	v_add_u32_e32 v30, 0xb800, v168
	v_mfma_f32_16x16x4_f32 v[116:119], v101, v83, v[116:119]
	ds_read2_b32 v[100:101], v30 offset0:192 offset1:208
	ds_read_b128 v[132:135], v54
	ds_read_b128 v[136:139], v81 offset:64
	ds_read_b128 v[140:143], v53 offset:64
	ds_read_b128 v[144:147], v55
	ds_read_b128 v[148:151], v54 offset:64
	ds_read_b128 v[152:155], v56
	ds_read_b128 v[156:159], v55 offset:64
	v_add_u32_e32 v30, 6, v42
	v_ashrrev_i32_e32 v31, 31, v30
	s_waitcnt lgkmcnt(8)
	v_mfma_f32_16x16x32_bf16 v[128:131], v[124:127], v[128:131], 0
	s_waitcnt lgkmcnt(6)
	v_mfma_f32_16x16x32_bf16 v[132:135], v[124:127], v[132:135], 0
	s_waitcnt lgkmcnt(3)
	v_mfma_f32_16x16x32_bf16 v[128:131], v[124:127], v[144:147], v[128:131]
	ds_read_b128 v[144:147], v56 offset:64
	s_waitcnt lgkmcnt(2)
	v_mfma_f32_16x16x32_bf16 v[124:127], v[124:127], v[152:155], v[132:135]
	s_nop 2
	v_add_u32_e32 v134, 7, v42
	v_ashrrev_i32_e32 v135, 31, v134
	v_mfma_f32_16x16x32_bf16 v[128:131], v[136:139], v[140:143], v[128:131]
	v_mfma_f32_16x16x32_bf16 v[124:127], v[136:139], v[148:151], v[124:127]
	v_mfma_f32_16x16x4_f32 v[120:123], v112, v100, v[120:123]
	v_mfma_f32_16x16x4_f32 v[116:119], v112, v101, v[116:119]
	global_load_ushort v111, v[208:209], off
	global_load_ushort v112, v[208:209], off offset:-3584
	global_load_dword v83, v[214:215], off offset:192
	global_load_ushort v100, v[212:213], off offset:2048
	global_load_ushort v101, v[208:209], off offset:3584
	global_load_ushort v102, v[208:209], off
	global_load_dword v81, v[214:215], off offset:224
	global_load_ushort v95, v[212:213], off offset:3072
	s_waitcnt lgkmcnt(1)
	v_mfma_f32_16x16x32_bf16 v[128:131], v[136:139], v[156:159], v[128:131]
	s_waitcnt lgkmcnt(0)
	v_mfma_f32_16x16x32_bf16 v[124:127], v[136:139], v[144:147], v[124:127]
	v_add_u32_e32 v136, 0xbc00, v168
	ds_read2_b32 v[132:133], v136 offset0:4 offset1:20
	ds_read2_b32 v[134:135], v136 offset0:72 offset1:88
	ds_read2_b32 v[136:137], v136 offset0:140 offset1:156
	s_nop 1
	s_waitcnt vmcnt(38)
	v_lshlrev_b32_e32 v179, 16, v185
	v_lshlrev_b32_e32 v177, 16, v187
	v_lshlrev_b32_e32 v178, 16, v188
	v_lshlrev_b32_e32 v182, 16, v189
	v_lshlrev_b32_e32 v184, 16, v191
	v_lshlrev_b32_e32 v181, 16, v190
	v_lshlrev_b32_e32 v183, 16, v192
	v_lshlrev_b32_e32 v180, 16, v186
	v_add_f32_e32 v128, v128, v177
	s_waitcnt lgkmcnt(2)
	v_mfma_f32_16x16x4_f32 v[120:123], v113, v132, v[120:123]
	v_add_f32_e32 v124, v124, v181
	v_add_u32_e32 v132, 0x4400, v78
	v_add_f32_e32 v129, v129, v178
	ds_write2_b32 v132, v128, v124 offset1:16
	v_add_f32_e32 v124, v125, v182
	v_add_f32_e32 v130, v130, v179
	ds_write2_b32 v132, v129, v124 offset0:68 offset1:84
	s_waitcnt lgkmcnt(3)
	v_mfma_f32_16x16x4_f32 v[120:123], v114, v134, v[120:123]
	v_add_f32_e32 v124, v126, v183
	v_add_f32_e32 v131, v131, v180
	ds_write2_b32 v132, v130, v124 offset0:136 offset1:152
	v_add_f32_e32 v124, v127, v184
	ds_write2_b32 v132, v131, v124 offset0:204 offset1:220
	s_waitcnt lgkmcnt(0)
	s_barrier
	v_mfma_f32_16x16x4_f32 v[120:123], v115, v136, v[120:123]
	v_mfma_f32_16x16x4_f32 v[116:119], v113, v133, v[116:119]
	s_waitcnt vmcnt(36)
	s_nop 7
	v_add_f32_e32 v120, v172, v120
	v_cvt_pk_bf16_f32 v124, v120, s0
	ds_write_b16 v57, v124
	v_lshlrev_b32_e32 v124, 16, v124
	v_sub_f32_e32 v124, v120, v124
	v_add_f32_e32 v113, v171, v121
	v_cvt_pk_bf16_f32 v124, v124, s0
	v_cvt_pk_bf16_f32 v121, v113, s0
	ds_write_b16 v58, v124
	ds_write_b16 v59, v121
	v_lshlrev_b32_e32 v121, 16, v121
	v_mfma_f32_16x16x4_f32 v[116:119], v114, v135, v[116:119]
	v_sub_f32_e32 v121, v113, v121
	v_cvt_pk_bf16_f32 v121, v121, s0
	ds_write_b16 v60, v121
	s_waitcnt vmcnt(33)
	v_add_f32_e32 v121, v175, v122
	v_cvt_pk_bf16_f32 v114, v121, s0
	ds_write_b16 v61, v114
	v_lshlrev_b32_e32 v114, 16, v114
	v_sub_f32_e32 v114, v121, v114
	v_cvt_pk_bf16_f32 v114, v114, s0
	ds_write_b16 v62, v114
	v_mfma_f32_16x16x4_f32 v[114:117], v115, v137, v[116:119]
	v_add_f32_e32 v118, v174, v123
	v_cvt_pk_bf16_f32 v119, v118, s0
	ds_write_b16 v63, v119
	v_lshlrev_b32_e32 v119, 16, v119
	v_sub_f32_e32 v119, v118, v119
	v_cvt_pk_bf16_f32 v119, v119, s0
	ds_write_b16 v64, v119
	s_nop 2
	v_add_f32_e32 v114, v173, v114
	v_cvt_pk_bf16_f32 v119, v114, s0
	ds_write_b16 v65, v119
	v_lshlrev_b32_e32 v119, 16, v119
	ds_write2_b32 v78, v120, v114 offset1:16
	v_sub_f32_e32 v114, v114, v119
	v_cvt_pk_bf16_f32 v114, v114, s0
	ds_write_b16 v66, v114
	v_add_f32_e32 v114, v169, v115
	ds_write2_b32 v78, v113, v114 offset0:68 offset1:84
	v_cvt_pk_bf16_f32 v113, v114, s0
	ds_write_b16 v67, v113
	v_lshlrev_b32_e32 v113, 16, v113
	v_sub_f32_e32 v113, v114, v113
	v_cvt_pk_bf16_f32 v113, v113, s0
	ds_write_b16 v68, v113
	s_waitcnt vmcnt(32)
	v_add_f32_e32 v113, v176, v116
	v_cvt_pk_bf16_f32 v114, v113, s0
	ds_write_b16 v69, v114
	v_lshlrev_b32_e32 v114, 16, v114
	ds_write2_b32 v78, v121, v113 offset0:136 offset1:152
	v_sub_f32_e32 v113, v113, v114
	v_cvt_pk_bf16_f32 v113, v113, s0
	ds_write_b16 v70, v113
	v_add_f32_e32 v113, v170, v117
	v_cvt_pk_bf16_f32 v114, v113, s0
	ds_write_b16 v71, v114
	v_lshlrev_b32_e32 v114, 16, v114
	ds_write2_b32 v78, v118, v113 offset0:204 offset1:220
	v_sub_f32_e32 v113, v113, v114
	v_cvt_pk_bf16_f32 v113, v113, s0
	ds_write_b16 v72, v113
	s_cbranch_vccnz .LBB0_1062
	s_bitcmp1_b32 s51, 0
	s_cselect_b32 s6, 0x4400, 0
	s_add_i32 s6, s6, 0
	v_add3_u32 v113, s6, v45, v46
	ds_write_b128 v113, v[10:13] offset:34816
	v_add3_u32 v10, s6, v47, v46
	s_add_i32 s6, s6, 0x19800
	ds_write_b128 v10, v[2:5] offset:34816
	v_add3_u32 v2, s6, v48, v49
	ds_write_b128 v2, v[6:9]
	s_branch .LBB0_1062
